# B-attention loop: last 3 P.V MFMA pairs of a tile deferred behind the next tile's barrier (their V fragments read 3 groups earlier into spare registers), filling the MFMA pipe while the next tile's fi
# speedup vs baseline: 1.0066x; 1.0066x over previous
; template <int DV, int NMAP> ...
;     ...
;             bf16x8 pf[2][2];
; #pragma unroll
;             for (int qb = 0; qb < 2; ++qb) {
; #pragma unroll
;                 for (int kb = 0; kb < 2; ++kb)
; #pragma unroll
;                     for (int i = 0; i < 4; ++i) s[kb][qb][i] = __builtin_amdgcn_exp2f(s[kb][qb][i]);
;                 v4u w; w.x = pg8::cvt_pk_bf16(s[0][qb][0], s[0][qb][1]); w.y = pg8::cvt_pk_bf16(s[0][qb][2], s[0][qb][3]);
;                 w.z = pg8::cvt_pk_bf16(s[1][qb][0], s[1][qb][1]); w.w = pg8::cvt_pk_bf16(s[1][qb][2], s[1][qb][3]); pf[qb][0] = __builtin_bit_cast(bf16x8, w);
;                 pf[qb][1] = pf[qb][0];
;             }
;             __builtin_amdgcn_sched_barrier(0);
; #pragma unroll
;             for (int i = 0; i < 2 * (DV / 16); ++i) {
;                 constexpr int NV = 2 * (DV / 16), EPS = 16 / (NV / 2);
;                 if (i == NV / 2) {
; #pragma unroll
;                     for (int qb = 0; qb < 2; ++qb) {
;                         v4u w; w.x = pg8::cvt_pk_bf16(s[2][qb][0], s[2][qb][1]); w.y = pg8::cvt_pk_bf16(s[2][qb][2], s[2][qb][3]);
;                         w.z = pg8::cvt_pk_bf16(s[3][qb][0], s[3][qb][1]); w.w = pg8::cvt_pk_bf16(s[3][qb][2], s[3][qb][3]); pf[qb][1] = __builtin_bit_cast(bf16x8, w);
;                         const f32x4 pa = (s[0][qb] + s[1][qb]) + (s[2][qb] + s[3][qb]);
;                         lsum[qb] += (pa[0] + pa[1]) + (pa[2] + pa[3]);
;                     }
;                 }
;                 bf16x8 cur = v0; v0 = v1; v1 = v2; if (i + 3 < NV) v2 = ATT_VLD(i + 3);
;                 if (i + 3 < NV) lgkm_pin<3>(cur); else if (i + 2 < NV) lgkm_pin<2>(cur); else if (i + 1 < NV) lgkm_pin<1>(cur); else lgkm_pin<0>(cur);
;                 __builtin_amdgcn_sched_barrier(0);
;                 o[i % (DV / 16)][0] = __builtin_amdgcn_mfma_f32_16x16x32_bf16(cur, pf[0][i / (DV / 16)], o[i % (DV / 16)][0], 0, 0, 0);
;                 o[i % (DV / 16)][1] = __builtin_amdgcn_mfma_f32_16x16x32_bf16(cur, pf[1][i / (DV / 16)], o[i % (DV / 16)][1], 0, 0, 0);
;                 if (i < NV / 2) {
; #pragma unroll
;                     for (int r_ = 0; r_ < EPS; ++r_) { const int e_ = i * EPS + r_; s[2 + (e_ >> 3)][(e_ >> 2) & 1][e_ & 3] = __builtin_amdgcn_exp2f(s[2 + (e_ >> 3)][(e_ >> 2) & 1][e_ & 3]); }
;                 }
;                 __builtin_amdgcn_sched_barrier(0);
;             }
.LBB0_318:
	v_exp_f32_e32 v222, v196
	v_exp_f32_e32 v223, v197
	v_exp_f32_e32 v196, v198
	v_exp_f32_e32 v197, v199
	v_exp_f32_e32 v198, v188
	v_exp_f32_e32 v199, v189
	v_exp_f32_e32 v190, v190
	v_exp_f32_e32 v191, v191
	v_cvt_pk_bf16_f32 v206, v222, v223
	v_cvt_pk_bf16_f32 v207, v196, v197
	v_cvt_pk_bf16_f32 v208, v198, v199
	v_cvt_pk_bf16_f32 v209, v190, v191
	v_exp_f32_e32 v188, v180
	v_exp_f32_e32 v189, v181
	v_exp_f32_e32 v180, v182
	v_exp_f32_e32 v181, v183
	v_exp_f32_e32 v182, v176
	v_exp_f32_e32 v183, v177
	v_exp_f32_e32 v176, v178
	v_exp_f32_e32 v177, v179
	v_cvt_pk_bf16_f32 v240, v188, v189
	v_cvt_pk_bf16_f32 v241, v180, v181
	v_cvt_pk_bf16_f32 v242, v182, v183
	v_cvt_pk_bf16_f32 v243, v176, v177
	ds_read_b128 v[244:247], v204 offset:0x1800
	s_waitcnt lgkmcnt(3)
	v_mfma_f32_16x16x32_bf16 v[156:159], v[200:203], v[206:209], v[156:159]
	v_exp_f32_e32 v178, v172
	v_mfma_f32_16x16x32_bf16 v[120:123], v[200:203], v[240:243], v[120:123]
	ds_read_b128 v[200:203], v204 offset:0x2000
	s_waitcnt lgkmcnt(3)
	v_mfma_f32_16x16x32_bf16 v[116:119], v[192:195], v[206:209], v[116:119]
	v_exp_f32_e32 v179, v173
	v_mfma_f32_16x16x32_bf16 v[112:115], v[192:195], v[240:243], v[112:115]
	ds_read_b128 v[192:195], v204 offset:0x2800
	s_waitcnt lgkmcnt(3)
	v_mfma_f32_16x16x32_bf16 v[108:111], v[184:187], v[206:209], v[108:111]
	v_exp_f32_e32 v248, v174
	v_mfma_f32_16x16x32_bf16 v[104:107], v[184:187], v[240:243], v[104:107]
	ds_read_b128 v[184:187], v204 offset:0x3000
	s_waitcnt lgkmcnt(3)
	v_mfma_f32_16x16x32_bf16 v[100:103], v[244:247], v[206:209], v[100:103]
	v_exp_f32_e32 v249, v175
	v_mfma_f32_16x16x32_bf16 v[96:99], v[244:247], v[240:243], v[96:99]
	ds_read_b128 v[172:175], v204 offset:0x3800
	s_waitcnt lgkmcnt(3)
	v_mfma_f32_16x16x32_bf16 v[92:95], v[200:203], v[206:209], v[92:95]
	v_exp_f32_e32 v244, v168
	v_mfma_f32_16x16x32_bf16 v[88:91], v[200:203], v[240:243], v[88:91]
	ds_read_b128 v[200:203], v204 offset:0x4000
	s_waitcnt lgkmcnt(3)
	v_mfma_f32_16x16x32_bf16 v[84:87], v[192:195], v[206:209], v[84:87]
	v_exp_f32_e32 v245, v169
	v_mfma_f32_16x16x32_bf16 v[80:83], v[192:195], v[240:243], v[80:83]
	ds_read_b128 v[192:195], v204 offset:0x4800
	s_waitcnt lgkmcnt(3)
	v_mfma_f32_16x16x32_bf16 v[76:79], v[184:187], v[206:209], v[76:79]
	v_exp_f32_e32 v246, v170
	v_mfma_f32_16x16x32_bf16 v[72:75], v[184:187], v[240:243], v[72:75]
	ds_read_b128 v[184:187], v204 offset:0x5000
	s_waitcnt lgkmcnt(3)
	v_mfma_f32_16x16x32_bf16 v[68:71], v[172:175], v[206:209], v[68:71]
	v_exp_f32_e32 v247, v171
	v_mfma_f32_16x16x32_bf16 v[64:67], v[172:175], v[240:243], v[64:67]
	ds_read_b128 v[168:171], v204 offset:0x5800
	s_waitcnt lgkmcnt(3)
	v_mfma_f32_16x16x32_bf16 v[60:63], v[200:203], v[206:209], v[60:63]
	v_mfma_f32_16x16x32_bf16 v[56:59], v[200:203], v[240:243], v[56:59]
	v_exp_f32_e32 v200, v164
	ds_read_b128 v[172:175], v204 offset:0x6000
	s_waitcnt lgkmcnt(3)
	v_mfma_f32_16x16x32_bf16 v[52:55], v[192:195], v[206:209], v[52:55]
	v_exp_f32_e32 v201, v165
	v_mfma_f32_16x16x32_bf16 v[48:51], v[192:195], v[240:243], v[48:51]
	ds_read_b128 v[192:195], v204 offset:0x6800
	s_waitcnt lgkmcnt(3)
	v_mfma_f32_16x16x32_bf16 v[44:47], v[184:187], v[206:209], v[44:47]
	v_exp_f32_e32 v202, v166
	v_mfma_f32_16x16x32_bf16 v[40:43], v[184:187], v[240:243], v[40:43]
	ds_read_b128 v[184:187], v204 offset:0x7000
	s_waitcnt lgkmcnt(3)
	v_mfma_f32_16x16x32_bf16 v[36:39], v[168:171], v[206:209], v[36:39]
	v_exp_f32_e32 v203, v167
	v_mfma_f32_16x16x32_bf16 v[32:35], v[168:171], v[240:243], v[32:35]
	ds_read_b128 v[164:167], v204 offset:0x7800
	s_waitcnt lgkmcnt(3)
	v_mfma_f32_16x16x32_bf16 v[28:31], v[172:175], v[206:209], v[28:31]
	v_exp_f32_e32 v250, v160
	v_mfma_f32_16x16x32_bf16 v[24:27], v[172:175], v[240:243], v[24:27]
	ds_read_b128 v[168:171], v204 offset:0x400
	s_waitcnt lgkmcnt(3)
	v_mfma_f32_16x16x32_bf16 v[20:23], v[192:195], v[206:209], v[20:23]
	v_exp_f32_e32 v251, v161
	v_mfma_f32_16x16x32_bf16 v[12:15], v[192:195], v[240:243], v[12:15]
	ds_read_b128 v[172:175], v204 offset:0xc00
	s_waitcnt lgkmcnt(3)
	v_mfma_f32_16x16x32_bf16 v[16:19], v[184:187], v[206:209], v[16:19]
	v_exp_f32_e32 v192, v162
	v_mfma_f32_16x16x32_bf16 v[8:11], v[184:187], v[240:243], v[8:11]
	ds_read_b128 v[184:187], v204 offset:0x1400
	s_waitcnt lgkmcnt(3)
; __device__ __forceinline__ unsigned cvt_pk_bf16(float lo, float hi) { unsigned r; asm volatile("v_cvt_pk_bf16_f32 %0, %1, %2" : "=v"(r) : "v"(lo), "v"(hi)); return r; }
; template <int N> __device__ __forceinline__ void lgkm_pin(bf16x8& f) { (void)f; asm volatile("s_waitcnt lgkmcnt(%0)" :: "n"(N) : "memory"); }
; #define ATT_VLD(i_) lds_rd(stv, ((((i_) % (DV / 16)) * 2) + ((i_) / (DV / 16))) * 1024)
; template <int DV, int NMAP> ...
;     ...
;                 if (i == NV / 2) {
; #pragma unroll
;                     for (int qb = 0; qb < 2; ++qb) {
;                         v4u w; w.x = pg8::cvt_pk_bf16(s[2][qb][0], s[2][qb][1]); w.y = pg8::cvt_pk_bf16(s[2][qb][2], s[2][qb][3]);
;                         w.z = pg8::cvt_pk_bf16(s[3][qb][0], s[3][qb][1]); w.w = pg8::cvt_pk_bf16(s[3][qb][2], s[3][qb][3]); pf[qb][1] = __builtin_bit_cast(bf16x8, w);
;                         const f32x4 pa = (s[0][qb] + s[1][qb]) + (s[2][qb] + s[3][qb]);
;                         lsum[qb] += (pa[0] + pa[1]) + (pa[2] + pa[3]);
;                     }
;                 }
;                 bf16x8 cur = v0; v0 = v1; v1 = v2; if (i + 3 < NV) v2 = ATT_VLD(i + 3);
;                 if (i + 3 < NV) lgkm_pin<3>(cur); else if (i + 2 < NV) lgkm_pin<2>(cur); else if (i + 1 < NV) lgkm_pin<1>(cur); else lgkm_pin<0>(cur);
;                 __builtin_amdgcn_sched_barrier(0);
;                 o[i % (DV / 16)][0] = __builtin_amdgcn_mfma_f32_16x16x32_bf16(cur, pf[0][i / (DV / 16)], o[i % (DV / 16)][0], 0, 0, 0);
;                 o[i % (DV / 16)][1] = __builtin_amdgcn_mfma_f32_16x16x32_bf16(cur, pf[1][i / (DV / 16)], o[i % (DV / 16)][1], 0, 0, 0);
;                 if (i < NV / 2) {
; #pragma unroll
;                     for (int r_ = 0; r_ < EPS; ++r_) { const int e_ = i * EPS + r_; s[2 + (e_ >> 3)][(e_ >> 2) & 1][e_ & 3] = __builtin_amdgcn_exp2f(s[2 + (e_ >> 3)][(e_ >> 2) & 1][e_ & 3]); }
;                 }
;                 __builtin_amdgcn_sched_barrier(0);
;             }
	v_mfma_f32_16x16x32_bf16 v[4:7], v[164:167], v[206:209], v[4:7]
	v_exp_f32_e32 v193, v163
	v_mfma_f32_16x16x32_bf16 v[0:3], v[164:167], v[240:243], v[0:3]
	v_add_f32_e64 v164, v198, v222
	v_add_f32_e64 v165, v199, v223
	v_pk_add_f32 v[166:167], v[190:191], v[196:197]
	v_cvt_pk_bf16_f32 v196, v178, v179
	v_pk_add_f32 v[178:179], v[200:201], v[178:179]
	v_pk_add_f32 v[190:191], v[202:203], v[248:249]
	v_pk_add_f32 v[182:183], v[182:183], v[188:189]
	v_pk_add_f32 v[176:177], v[176:177], v[180:181]
	v_pk_add_f32 v[180:181], v[250:251], v[244:245]
	v_pk_add_f32 v[188:189], v[192:193], v[246:247]
	v_pk_add_f32 v[190:191], v[190:191], v[166:167]
	v_pk_add_f32 v[178:179], v[178:179], v[164:165]
	v_pk_add_f32 v[176:177], v[188:189], v[176:177]
	v_pk_add_f32 v[180:181], v[180:181], v[182:183]
	v_mov_b32_e32 v183, v178
	v_mov_b32_e32 v182, v180
	v_mov_b32_e32 v178, v181
	v_mov_b32_e32 v180, v176
	v_mov_b32_e32 v181, v190
	v_mov_b32_e32 v190, v177
	v_pk_add_f32 v[178:179], v[182:183], v[178:179]
	v_pk_add_f32 v[176:177], v[180:181], v[190:191]
	v_cvt_pk_bf16_f32 v197, v248, v249
	v_cvt_pk_bf16_f32 v198, v200, v201
	v_cvt_pk_bf16_f32 v199, v202, v203
	v_cvt_pk_bf16_f32 v200, v244, v245
	v_cvt_pk_bf16_f32 v201, v246, v247
	s_nop 0
	v_pk_add_f32 v[176:177], v[178:179], v[176:177]
	v_cvt_pk_bf16_f32 v202, v250, v251
	v_cvt_pk_bf16_f32 v203, v192, v193
	s_nop 0
	v_pk_add_f32 v[218:219], v[218:219], v[176:177]
	ds_read_b128 v[176:179], v204 offset:0x1c00
	s_waitcnt lgkmcnt(3)
	v_mfma_f32_16x16x32_bf16 v[156:159], v[168:171], v[196:199], v[156:159]
	v_mfma_f32_16x16x32_bf16 v[120:123], v[168:171], v[200:203], v[120:123]
	ds_read_b128 v[168:171], v204 offset:0x2400
	s_waitcnt lgkmcnt(3)
	v_mfma_f32_16x16x32_bf16 v[116:119], v[172:175], v[196:199], v[116:119]
	v_mfma_f32_16x16x32_bf16 v[112:115], v[172:175], v[200:203], v[112:115]
	ds_read_b128 v[172:175], v204 offset:0x2c00
	s_waitcnt lgkmcnt(3)
	v_mfma_f32_16x16x32_bf16 v[108:111], v[184:187], v[196:199], v[108:111]
	v_mfma_f32_16x16x32_bf16 v[104:107], v[184:187], v[200:203], v[104:107]
	ds_read_b128 v[180:183], v204 offset:0x3400
	s_waitcnt lgkmcnt(3)
	v_mfma_f32_16x16x32_bf16 v[100:103], v[176:179], v[196:199], v[100:103]
	v_mfma_f32_16x16x32_bf16 v[96:99], v[176:179], v[200:203], v[96:99]
	ds_read_b128 v[176:179], v204 offset:0x3c00
	s_waitcnt lgkmcnt(3)
	v_mfma_f32_16x16x32_bf16 v[92:95], v[168:171], v[196:199], v[92:95]
	v_mfma_f32_16x16x32_bf16 v[88:91], v[168:171], v[200:203], v[88:91]
	ds_read_b128 v[168:171], v204 offset:0x4400
	s_waitcnt lgkmcnt(3)
	v_mfma_f32_16x16x32_bf16 v[84:87], v[172:175], v[196:199], v[84:87]
	v_mfma_f32_16x16x32_bf16 v[80:83], v[172:175], v[200:203], v[80:83]
	ds_read_b128 v[172:175], v204 offset:0x4c00
	s_waitcnt lgkmcnt(3)
	v_mfma_f32_16x16x32_bf16 v[76:79], v[180:183], v[196:199], v[76:79]
	v_mfma_f32_16x16x32_bf16 v[72:75], v[180:183], v[200:203], v[72:75]
	ds_read_b128 v[180:183], v204 offset:0x5400
	ds_read_b128 v[184:187], v204 offset:0x6c00
	s_waitcnt lgkmcnt(4)
	v_mfma_f32_16x16x32_bf16 v[68:71], v[176:179], v[196:199], v[68:71]
	v_mfma_f32_16x16x32_bf16 v[64:67], v[176:179], v[200:203], v[64:67]
	ds_read_b128 v[176:179], v204 offset:0x5c00
	ds_read_b128 v[188:191], v204 offset:0x7400
	s_waitcnt lgkmcnt(5)
	v_mfma_f32_16x16x32_bf16 v[60:63], v[168:171], v[196:199], v[60:63]
	v_mfma_f32_16x16x32_bf16 v[56:59], v[168:171], v[200:203], v[56:59]
	ds_read_b128 v[168:171], v204 offset:0x6400
	ds_read_b128 v[192:195], v204 offset:0x7c00
	s_waitcnt lgkmcnt(6)
	v_mfma_f32_16x16x32_bf16 v[52:55], v[172:175], v[196:199], v[52:55]
	v_mfma_f32_16x16x32_bf16 v[48:51], v[172:175], v[200:203], v[48:51]
	s_waitcnt lgkmcnt(5)
	v_mfma_f32_16x16x32_bf16 v[44:47], v[180:183], v[196:199], v[44:47]
	v_mfma_f32_16x16x32_bf16 v[40:43], v[180:183], v[200:203], v[40:43]
	s_waitcnt lgkmcnt(3)
	v_mfma_f32_16x16x32_bf16 v[36:39], v[176:179], v[196:199], v[36:39]
	v_mfma_f32_16x16x32_bf16 v[32:35], v[176:179], v[200:203], v[32:35]
	s_waitcnt lgkmcnt(1)
	v_mfma_f32_16x16x32_bf16 v[28:31], v[168:171], v[196:199], v[28:31]
	v_mfma_f32_16x16x32_bf16 v[24:27], v[168:171], v[200:203], v[24:27]

; template <int N> __device__ __forceinline__ void lgkm_pin(bf16x8& f) { (void)f; asm volatile("s_waitcnt lgkmcnt(%0)" :: "n"(N) : "memory"); }
; #define ATT_STAGE(t_, buf_) do { const char* gb_ = gbase + (size_t)(t_) * tstep; _Pragma("unroll") for (int j_ = 0; j_ < NPW * REP_DMA; ++j_) \
;         __builtin_amdgcn_global_load_lds((const unsigned*)(gb_ + ATT_CJ(j_ % NPW) + vbase), (LAS unsigned*)(lds + (buf_) * STAGE + (wid * NPW + j_ % NPW) * 1024), 16, 0, 0); } while (0)
; #define ATT_KLD(i_) lds_rd(stk, (((i_) >> 2) >> 1) * 8192 + (((i_) & 3) * 2 + (((i_) >> 2) & 1)) * 1024)
; #define ATT_VLD(i_) lds_rd(stv, ((((i_) % (DV / 16)) * 2) + ((i_) / (DV / 16))) * 1024)
; template <int DV, int NMAP> ...
;     ...
;             { bf16x8 f0 = ATT_KLD(0), f1 = ATT_KLD(1), f2 = ATT_KLD(2);
; #pragma unroll
;               for (int i = 0; i < 16; ++i) {
;                   bf16x8 cur = f0; f0 = f1; f1 = f2; if (i + 3 < 16) f2 = ATT_KLD(i + 3);
;                   if (i + 3 < 16) lgkm_pin<3>(cur); else if (i + 2 < 16) lgkm_pin<2>(cur); else if (i + 1 < 16) lgkm_pin<1>(cur); else lgkm_pin<0>(cur);
;                   __builtin_amdgcn_sched_barrier(0);
;                   s[i & 3][0] = __builtin_amdgcn_mfma_f32_16x16x32_bf16(cur, q[0][i >> 2], s[i & 3][0], 0, 0, 0);
;                   s[i & 3][1] = __builtin_amdgcn_mfma_f32_16x16x32_bf16(cur, q[1][i >> 2], s[i & 3][1], 0, 0, 0);
;                   __builtin_amdgcn_sched_barrier(0);
;               } }
;             if (t < T1 && !isk) ATT_STAGE(t + 1, cur ^ 1);
;     ...
;                 bf16x8 cur = v0; v0 = v1; v1 = v2; if (i + 3 < NV) v2 = ATT_VLD(i + 3);
;                 if (i + 3 < NV) lgkm_pin<3>(cur); else if (i + 2 < NV) lgkm_pin<2>(cur); else if (i + 1 < NV) lgkm_pin<1>(cur); else lgkm_pin<0>(cur);
;                 __builtin_amdgcn_sched_barrier(0);
;                 o[i % (DV / 16)][0] = __builtin_amdgcn_mfma_f32_16x16x32_bf16(cur, pf[0][i / (DV / 16)], o[i % (DV / 16)][0], 0, 0, 0);
;                 o[i % (DV / 16)][1] = __builtin_amdgcn_mfma_f32_16x16x32_bf16(cur, pf[1][i / (DV / 16)], o[i % (DV / 16)][1], 0, 0, 0);
.LBB0_322:
	s_andn2_b64 vcc, exec, s[44:45]
	s_cbranch_vccnz .Lbt_skip
	s_lshl_b32 s45, s52, 16
	s_add_i32 s44, s45, 0
	s_add_i32 s52, s44, s57
	v_add_u32_e32 v204, s52, v238
	ds_read_b128 v[160:163], v204 offset:0
	ds_read_b128 v[164:167], v204 offset:0x800
	ds_read_b128 v[168:171], v204 offset:0x1000
	ds_read_b128 v[172:175], v204 offset:0x1800
	s_add_i32 s53, s84, -1
	s_cmp_le_u32 s53, s37
	s_cbranch_scc0 .Lbt_qk
	v_mfma_f32_16x16x32_bf16 v[20:23], v[184:187], v[196:199], v[20:23]
	v_mfma_f32_16x16x32_bf16 v[12:15], v[184:187], v[200:203], v[12:15]
	v_mfma_f32_16x16x32_bf16 v[16:19], v[188:191], v[196:199], v[16:19]
	v_mfma_f32_16x16x32_bf16 v[8:11], v[188:191], v[200:203], v[8:11]
	v_mfma_f32_16x16x32_bf16 v[4:7], v[192:195], v[196:199], v[4:7]
	v_mfma_f32_16x16x32_bf16 v[0:3], v[192:195], v[200:203], v[0:3]
.Lbt_qk:
	s_waitcnt lgkmcnt(3)
	s_nop 0
	v_mfma_f32_16x16x32_bf16 v[176:179], v[160:163], v[124:127], 0
	v_mfma_f32_16x16x32_bf16 v[160:163], v[160:163], v[140:143], 0
	ds_read_b128 v[180:183], v204 offset:0x400
	s_waitcnt lgkmcnt(3)
	v_mfma_f32_16x16x32_bf16 v[184:187], v[164:167], v[124:127], 0
	v_mfma_f32_16x16x32_bf16 v[164:167], v[164:167], v[140:143], 0
	ds_read_b128 v[188:191], v204 offset:0xc00
	s_waitcnt lgkmcnt(3)
	v_mfma_f32_16x16x32_bf16 v[192:195], v[168:171], v[124:127], 0
	v_mfma_f32_16x16x32_bf16 v[168:171], v[168:171], v[140:143], 0
	ds_read_b128 v[196:199], v204 offset:0x1400
	s_waitcnt lgkmcnt(3)
	v_mfma_f32_16x16x32_bf16 v[200:203], v[172:175], v[124:127], 0
	v_mfma_f32_16x16x32_bf16 v[172:175], v[172:175], v[140:143], 0
	ds_read_b128 v[240:243], v204 offset:0x1c00
	s_waitcnt lgkmcnt(3)
	v_mfma_f32_16x16x32_bf16 v[176:179], v[180:183], v[128:131], v[176:179]
	v_mfma_f32_16x16x32_bf16 v[160:163], v[180:183], v[144:147], v[160:163]
	ds_read_b128 v[180:183], v204 offset:0x2000
	s_waitcnt lgkmcnt(3)
	v_mfma_f32_16x16x32_bf16 v[164:167], v[188:191], v[144:147], v[164:167]
	v_mfma_f32_16x16x32_bf16 v[184:187], v[188:191], v[128:131], v[184:187]
	ds_read_b128 v[188:191], v204 offset:0x2800
	s_waitcnt lgkmcnt(3)
	v_mfma_f32_16x16x32_bf16 v[168:171], v[196:199], v[144:147], v[168:171]
	v_mfma_f32_16x16x32_bf16 v[192:195], v[196:199], v[128:131], v[192:195]
	ds_read_b128 v[196:199], v204 offset:0x3000
	s_waitcnt lgkmcnt(3)
	v_mfma_f32_16x16x32_bf16 v[172:175], v[240:243], v[144:147], v[172:175]
	v_mfma_f32_16x16x32_bf16 v[200:203], v[240:243], v[128:131], v[200:203]
	ds_read_b128 v[240:243], v204 offset:0x3800
	s_waitcnt lgkmcnt(3)
	v_mfma_f32_16x16x32_bf16 v[176:179], v[180:183], v[132:135], v[176:179]
	v_mfma_f32_16x16x32_bf16 v[160:163], v[180:183], v[148:151], v[160:163]
	ds_read_b128 v[180:183], v204 offset:0x2400
	s_waitcnt lgkmcnt(3)
	v_mfma_f32_16x16x32_bf16 v[164:167], v[188:191], v[148:151], v[164:167]
	v_mfma_f32_16x16x32_bf16 v[184:187], v[188:191], v[132:135], v[184:187]
	ds_read_b128 v[244:247], v204 offset:0x2c00
	s_waitcnt lgkmcnt(3)
	v_mfma_f32_16x16x32_bf16 v[168:171], v[196:199], v[148:151], v[168:171]
	v_mfma_f32_16x16x32_bf16 v[192:195], v[196:199], v[132:135], v[192:195]
	ds_read_b128 v[248:251], v204 offset:0x3400
	s_waitcnt lgkmcnt(3)
	v_mfma_f32_16x16x32_bf16 v[200:203], v[240:243], v[132:135], v[200:203]
	v_mfma_f32_16x16x32_bf16 v[240:243], v[240:243], v[148:151], v[172:175]
	ds_read_b128 v[206:209], v204 offset:0x3c00
	s_waitcnt lgkmcnt(3)
	v_mfma_f32_16x16x32_bf16 v[196:199], v[180:183], v[136:139], v[176:179]
	v_mfma_f32_16x16x32_bf16 v[180:183], v[180:183], v[152:155], v[160:163]
	s_waitcnt lgkmcnt(2)
	v_mfma_f32_16x16x32_bf16 v[188:191], v[244:247], v[136:139], v[184:187]
	v_mfma_f32_16x16x32_bf16 v[176:179], v[244:247], v[152:155], v[164:167]
	s_waitcnt lgkmcnt(1)
	v_mfma_f32_16x16x32_bf16 v[172:175], v[248:251], v[136:139], v[192:195]
	v_mfma_f32_16x16x32_bf16 v[168:171], v[248:251], v[152:155], v[168:171]
	s_waitcnt lgkmcnt(0)
	v_mfma_f32_16x16x32_bf16 v[164:167], v[206:209], v[136:139], v[200:203]
	v_mfma_f32_16x16x32_bf16 v[160:163], v[206:209], v[152:155], v[240:243]
	s_cmp_gt_u32 s84, s35
	s_cselect_b64 s[52:53], -1, 0
	s_or_b64 s[52:53], s[4:5], s[52:53]
	s_and_b64 vcc, exec, s[52:53]
	s_cbranch_vccnz .LBB0_325
	s_xor_b32 s45, s45, 0x10000
	s_add_i32 s45, s34, s45
	s_mov_b32 m0, s45
	v_lshl_add_u64 v[184:185], v[220:221], 0, 64
	global_load_lds_dwordx4 v[220:221], off
	s_add_i32 m0, s45, 0x400
	s_mov_b64 s[52:53], 0x100040
	global_load_lds_dwordx4 v[184:185], off
	v_lshl_add_u64 v[184:185], v[220:221], 0, s[24:25]
	s_add_i32 m0, s45, 0x800
	s_nop 0
	global_load_lds_dwordx4 v[184:185], off
	v_lshl_add_u64 v[184:185], v[220:221], 0, s[12:13]
	s_add_i32 m0, s45, 0xc00
	s_nop 0
	global_load_lds_dwordx4 v[184:185], off
	v_lshl_add_u64 v[184:185], v[220:221], 0, s[30:31]
	s_add_i32 m0, s45, 0x1000
	s_nop 0
	global_load_lds_dwordx4 v[184:185], off
	v_lshl_add_u64 v[184:185], v[220:221], 0, s[52:53]
	s_add_i32 m0, s45, 0x1400
	s_mov_b64 s[52:53], 0x180000
	global_load_lds_dwordx4 v[184:185], off
	v_lshl_add_u64 v[184:185], v[220:221], 0, s[52:53]
	s_add_i32 m0, s45, 0x1800
	s_mov_b64 s[52:53], 0x180040
	global_load_lds_dwordx4 v[184:185], off
	v_lshl_add_u64 v[184:185], v[220:221], 0, s[52:53]
	s_add_i32 m0, s45, 0x1c00
	s_nop 0
	global_load_lds_dwordx4 v[184:185], off

; __device__ __forceinline__ unsigned cvt_pk_bf16(float lo, float hi) { unsigned r; asm volatile("v_cvt_pk_bf16_f32 %0, %1, %2" : "=v"(r) : "v"(lo), "v"(hi)); return r; }
; template <int N> __device__ __forceinline__ void lgkm_pin(bf16x8& f) { (void)f; asm volatile("s_waitcnt lgkmcnt(%0)" :: "n"(N) : "memory"); }
; #define ATT_VLD(i_) lds_rd(stv, ((((i_) % (DV / 16)) * 2) + ((i_) / (DV / 16))) * 1024)
; template <int DV, int NMAP> ...
;     ...
;             for (int i = 0; i < 2 * (DV / 16); ++i) {
;                 constexpr int NV = 2 * (DV / 16), EPS = 16 / (NV / 2);
;                 if (i == NV / 2) {
; #pragma unroll
;                     for (int qb = 0; qb < 2; ++qb) {
;                         v4u w; w.x = pg8::cvt_pk_bf16(s[2][qb][0], s[2][qb][1]); w.y = pg8::cvt_pk_bf16(s[2][qb][2], s[2][qb][3]);
;                         w.z = pg8::cvt_pk_bf16(s[3][qb][0], s[3][qb][1]); w.w = pg8::cvt_pk_bf16(s[3][qb][2], s[3][qb][3]); pf[qb][1] = __builtin_bit_cast(bf16x8, w);
;                         const f32x4 pa = (s[0][qb] + s[1][qb]) + (s[2][qb] + s[3][qb]);
;                         lsum[qb] += (pa[0] + pa[1]) + (pa[2] + pa[3]);
;                     }
;                 }
;                 bf16x8 cur = v0; v0 = v1; v1 = v2; if (i + 3 < NV) v2 = ATT_VLD(i + 3);
;                 if (i + 3 < NV) lgkm_pin<3>(cur); else if (i + 2 < NV) lgkm_pin<2>(cur); else if (i + 1 < NV) lgkm_pin<1>(cur); else lgkm_pin<0>(cur);
;                 __builtin_amdgcn_sched_barrier(0);
;                 o[i % (DV / 16)][0] = __builtin_amdgcn_mfma_f32_16x16x32_bf16(cur, pf[0][i / (DV / 16)], o[i % (DV / 16)][0], 0, 0, 0);
;                 o[i % (DV / 16)][1] = __builtin_amdgcn_mfma_f32_16x16x32_bf16(cur, pf[1][i / (DV / 16)], o[i % (DV / 16)][1], 0, 0, 0);
;                 if (i < NV / 2) {
; #pragma unroll
;                     for (int r_ = 0; r_ < EPS; ++r_) { const int e_ = i * EPS + r_; s[2 + (e_ >> 3)][(e_ >> 2) & 1][e_ & 3] = __builtin_amdgcn_exp2f(s[2 + (e_ >> 3)][(e_ >> 2) & 1][e_ & 3]); }
;                 }
;                 __builtin_amdgcn_sched_barrier(0);
;             }
.Lbt_skip:
	s_add_i32 s53, s84, -1
	s_cmp_le_u32 s53, s37
	s_cbranch_scc0 .LBB0_319
	v_mfma_f32_16x16x32_bf16 v[20:23], v[184:187], v[196:199], v[20:23]
	v_mfma_f32_16x16x32_bf16 v[12:15], v[184:187], v[200:203], v[12:15]
	v_mfma_f32_16x16x32_bf16 v[16:19], v[188:191], v[196:199], v[16:19]
	v_mfma_f32_16x16x32_bf16 v[8:11], v[188:191], v[200:203], v[8:11]
	v_mfma_f32_16x16x32_bf16 v[4:7], v[192:195], v[196:199], v[4:7]
	v_mfma_f32_16x16x32_bf16 v[0:3], v[192:195], v[200:203], v[0:3]
	s_branch .LBB0_319
.LBB0_327:
	s_add_i32 s53, s84, -1
	s_cmp_le_u32 s53, s37
	s_cbranch_scc0 .Lbt_exit
	s_waitcnt lgkmcnt(0)
	v_mfma_f32_16x16x32_bf16 v[20:23], v[184:187], v[196:199], v[20:23]
	v_mfma_f32_16x16x32_bf16 v[12:15], v[184:187], v[200:203], v[12:15]
	v_mfma_f32_16x16x32_bf16 v[16:19], v[188:191], v[196:199], v[16:19]
	v_mfma_f32_16x16x32_bf16 v[8:11], v[188:191], v[200:203], v[8:11]
	v_mfma_f32_16x16x32_bf16 v[4:7], v[192:195], v[196:199], v[4:7]
	v_mfma_f32_16x16x32_bf16 v[0:3], v[192:195], v[200:203], v[0:3]
	s_nop 7
	s_nop 7
